# branch A: A-fragment ds_reads batched once per group ahead of the MFMA chain (both t-blocks reuse them)
# speedup vs baseline: 1.0054x; 1.0054x over previous
; __device__ __forceinline__ u32x4 pack8(const f32x4 a, const f32x4 b) { u32x4 w; w.x = cvt_pk_bf16(a[0], a[1]); w.y = cvt_pk_bf16(a[2], a[3]); w.z = cvt_pk_bf16(b[0], b[1]); w.w = cvt_pk_bf16(b[2], b[3]); return w; }
; #define LAS __attribute__((address_space(3)))
;     ...
;     for (int g = 0; g < 8; ++g) {
;         const f32x4 ga = *(const LAS f32x4*)(gbl + g * 128 + (tid & 15) * 8), gb2 = *(const LAS f32x4*)(gbl + g * 128 + (tid & 15) * 8 + 4);
;         const f32x4 ba = *(const LAS f32x4*)(gbl + 1024 + g * 128 + (tid & 15) * 8), bb2 = *(const LAS f32x4*)(gbl + 1024 + g * 128 + (tid & 15) * 8 + 4);
; #pragma unroll
;         for (int i = 0; i < 4; ++i) {
;             const int p = tid + 512 * i, s = p >> 4, dc = p & 15;
;             f32x4 v0, v1; pg8::unpack8(vpc[i], v0, v1);
;             const float mean = stat[s * 2], rstd = stat[s * 2 + 1];
;             v0 = (v0 - mean) * rstd * ga + ba; v1 = (v1 - mean) * rstd * gb2 + bb2;
;             const u32x4 w = pg8::pack8(v0, v1);
;             LAS unsigned short* dst = (LAS unsigned short*)(lds + BA_VNT) + dc * 136 + s;
;             dst[0 * 16 * 136] = (unsigned short)(w.x & 0xffffu); dst[1 * 16 * 136] = (unsigned short)(w.x >> 16); dst[2 * 16 * 136] = (unsigned short)(w.y & 0xffffu); dst[3 * 16 * 136] = (unsigned short)(w.y >> 16);
;             dst[4 * 16 * 136] = (unsigned short)(w.z & 0xffffu); dst[5 * 16 * 136] = (unsigned short)(w.z >> 16); dst[6 * 16 * 136] = (unsigned short)(w.w & 0xffffu); dst[7 * 16 * 136] = (unsigned short)(w.w >> 16);
;         }
;         if (g + 1 < 8) {
; #pragma unroll
;             for (int i = 0; i < 4; ++i) { const int p = tid + 512 * i, s = p >> 4, dc = p & 15; vpc[i] = *(const u32x4*)(Vb + (t0 + s) * 1024 + (g + 1) * 128 + dc * 8); }
;         }
;         __syncthreads();
.LBB0_510:
	ds_read_b128 v[8:11], v176
	ds_read_b128 v[0:3], v176 offset:16
	ds_read_b128 v[12:15], v176 offset:4096
	ds_read_b128 v[4:7], v176 offset:4112
	ds_read_b64 v[16:17], v177
	v_lshlrev_b32_e32 v20, 16, v126
	v_and_b32_e32 v21, 0xffff0000, v126
	v_lshlrev_b32_e32 v18, 16, v127
	v_and_b32_e32 v19, 0xffff0000, v127
	v_lshlrev_b32_e32 v24, 16, v128
	v_and_b32_e32 v25, 0xffff0000, v128
	v_lshlrev_b32_e32 v22, 16, v129
	v_and_b32_e32 v23, 0xffff0000, v129
	s_waitcnt lgkmcnt(0)
	v_sub_f32_e32 v21, v21, v16
	v_sub_f32_e32 v20, v20, v16
	v_sub_f32_e32 v19, v19, v16
	v_sub_f32_e32 v18, v18, v16
	v_pk_mul_f32 v[20:21], v[16:17], v[20:21] op_sel:[1,0]
	v_sub_f32_e32 v23, v23, v16
	v_sub_f32_e32 v22, v22, v16
	v_sub_f32_e32 v25, v25, v16
	v_sub_f32_e32 v24, v24, v16
	v_pk_mul_f32 v[18:19], v[16:17], v[18:19] op_sel:[1,0]
	v_pk_fma_f32 v[20:21], v[8:9], v[20:21], v[12:13]
	v_pk_mul_f32 v[24:25], v[16:17], v[24:25] op_sel:[1,0]
	v_pk_mul_f32 v[16:17], v[16:17], v[22:23] op_sel:[1,0]
	v_pk_fma_f32 v[18:19], v[10:11], v[18:19], v[14:15]
	v_pk_fma_f32 v[16:17], v[2:3], v[16:17], v[6:7]
	v_pk_fma_f32 v[22:23], v[0:1], v[24:25], v[4:5]
	v_cvt_pk_bf16_f32 v20, v20, v21
	v_cvt_pk_bf16_f32 v18, v18, v19
	v_cvt_pk_bf16_f32 v19, v22, v23
	v_cvt_pk_bf16_f32 v16, v16, v17
	ds_write_b16 v174, v20 offset:9216
	ds_write_b16_d16_hi v174, v20 offset:13568
	ds_write_b16 v174, v18 offset:17920
	ds_write_b16_d16_hi v174, v18 offset:22272
	ds_write_b16 v174, v19 offset:26624
	ds_write_b16_d16_hi v174, v19 offset:30976
	ds_write_b16 v174, v16 offset:35328
	ds_write_b16_d16_hi v174, v16 offset:39680
	ds_read_b64 v[16:17], v173
	v_lshlrev_b32_e32 v20, 16, v122
	v_and_b32_e32 v21, 0xffff0000, v122
	v_lshlrev_b32_e32 v18, 16, v123
	v_and_b32_e32 v19, 0xffff0000, v123
	v_lshlrev_b32_e32 v24, 16, v124
	v_and_b32_e32 v25, 0xffff0000, v124
	v_lshlrev_b32_e32 v22, 16, v125
	v_and_b32_e32 v23, 0xffff0000, v125
	s_waitcnt lgkmcnt(0)
	v_sub_f32_e32 v21, v21, v16
	v_sub_f32_e32 v20, v20, v16
	v_sub_f32_e32 v19, v19, v16
	v_sub_f32_e32 v18, v18, v16
	v_pk_mul_f32 v[20:21], v[16:17], v[20:21] op_sel:[1,0]
	v_sub_f32_e32 v23, v23, v16
	v_sub_f32_e32 v22, v22, v16
	v_sub_f32_e32 v25, v25, v16
	v_sub_f32_e32 v24, v24, v16
	v_pk_mul_f32 v[18:19], v[16:17], v[18:19] op_sel:[1,0]
	v_pk_fma_f32 v[20:21], v[8:9], v[20:21], v[12:13]
	v_pk_mul_f32 v[24:25], v[16:17], v[24:25] op_sel:[1,0]
	v_pk_mul_f32 v[16:17], v[16:17], v[22:23] op_sel:[1,0]
	v_pk_fma_f32 v[18:19], v[10:11], v[18:19], v[14:15]
	v_pk_fma_f32 v[16:17], v[2:3], v[16:17], v[6:7]
	v_pk_fma_f32 v[22:23], v[0:1], v[24:25], v[4:5]
	v_cvt_pk_bf16_f32 v20, v20, v21
	v_cvt_pk_bf16_f32 v18, v18, v19
	v_cvt_pk_bf16_f32 v19, v22, v23
	v_cvt_pk_bf16_f32 v16, v16, v17
	ds_write_b16 v172, v20 offset:9216
	ds_write_b16_d16_hi v172, v20 offset:13568
	ds_write_b16 v172, v18 offset:17920
	ds_write_b16_d16_hi v172, v18 offset:22272
	ds_write_b16 v172, v19 offset:26624
	ds_write_b16_d16_hi v172, v19 offset:30976
	ds_write_b16 v172, v16 offset:35328
	ds_write_b16_d16_hi v172, v16 offset:39680
	ds_read_b64 v[16:17], v171
	s_waitcnt vmcnt(5)
	v_lshlrev_b32_e32 v20, 16, v118
	v_and_b32_e32 v21, 0xffff0000, v118
	v_lshlrev_b32_e32 v18, 16, v119
	v_and_b32_e32 v19, 0xffff0000, v119
	v_lshlrev_b32_e32 v24, 16, v120
	v_and_b32_e32 v25, 0xffff0000, v120
	v_lshlrev_b32_e32 v22, 16, v121
	v_and_b32_e32 v23, 0xffff0000, v121
	s_waitcnt lgkmcnt(0)
	v_sub_f32_e32 v21, v21, v16
	v_sub_f32_e32 v20, v20, v16
	v_sub_f32_e32 v19, v19, v16
	v_sub_f32_e32 v18, v18, v16
	v_pk_mul_f32 v[20:21], v[16:17], v[20:21] op_sel:[1,0]
	v_sub_f32_e32 v23, v23, v16
	v_sub_f32_e32 v22, v22, v16
	v_sub_f32_e32 v25, v25, v16
	v_sub_f32_e32 v24, v24, v16
	v_pk_mul_f32 v[18:19], v[16:17], v[18:19] op_sel:[1,0]
	v_pk_fma_f32 v[20:21], v[8:9], v[20:21], v[12:13]
	v_pk_mul_f32 v[24:25], v[16:17], v[24:25] op_sel:[1,0]
	v_pk_mul_f32 v[16:17], v[16:17], v[22:23] op_sel:[1,0]
	v_pk_fma_f32 v[18:19], v[10:11], v[18:19], v[14:15]
	v_pk_fma_f32 v[16:17], v[2:3], v[16:17], v[6:7]
	v_pk_fma_f32 v[22:23], v[0:1], v[24:25], v[4:5]
	v_cvt_pk_bf16_f32 v20, v20, v21
	v_cvt_pk_bf16_f32 v18, v18, v19
	v_cvt_pk_bf16_f32 v19, v22, v23
	v_cvt_pk_bf16_f32 v16, v16, v17
	ds_write_b16 v170, v20 offset:9216
	ds_write_b16_d16_hi v170, v20 offset:13568
	ds_write_b16 v170, v18 offset:17920
	ds_write_b16_d16_hi v170, v18 offset:22272
	ds_write_b16 v170, v19 offset:26624
	ds_write_b16_d16_hi v170, v19 offset:30976
	ds_write_b16 v170, v16 offset:35328
	ds_write_b16_d16_hi v170, v16 offset:39680
	ds_read_b64 v[16:17], v169
	s_waitcnt vmcnt(4)
	v_lshlrev_b32_e32 v20, 16, v114
	v_and_b32_e32 v21, 0xffff0000, v114
	v_lshlrev_b32_e32 v18, 16, v115
	v_and_b32_e32 v19, 0xffff0000, v115
	s_waitcnt lgkmcnt(0)
	v_sub_f32_e32 v19, v19, v16
	v_sub_f32_e32 v18, v18, v16
	v_sub_f32_e32 v21, v21, v16
	v_sub_f32_e32 v20, v20, v16
	v_lshlrev_b32_e32 v22, 16, v116
	v_and_b32_e32 v23, 0xffff0000, v116
	v_lshlrev_b32_e32 v24, 16, v117
	v_and_b32_e32 v25, 0xffff0000, v117
	v_pk_mul_f32 v[20:21], v[16:17], v[20:21] op_sel:[1,0]
	v_pk_mul_f32 v[18:19], v[16:17], v[18:19] op_sel:[1,0]
	v_pk_fma_f32 v[8:9], v[8:9], v[20:21], v[12:13]
	v_pk_fma_f32 v[10:11], v[10:11], v[18:19], v[14:15]
	v_sub_f32_e32 v13, v25, v16
	v_sub_f32_e32 v12, v24, v16
	v_sub_f32_e32 v15, v23, v16
	v_sub_f32_e32 v14, v22, v16
	v_pk_mul_f32 v[14:15], v[16:17], v[14:15] op_sel:[1,0]
	v_pk_mul_f32 v[12:13], v[16:17], v[12:13] op_sel:[1,0]
	v_pk_fma_f32 v[0:1], v[0:1], v[14:15], v[4:5]
	v_pk_fma_f32 v[2:3], v[2:3], v[12:13], v[6:7]
	v_cvt_pk_bf16_f32 v4, v8, v9
	v_cvt_pk_bf16_f32 v0, v0, v1
	v_cvt_pk_bf16_f32 v1, v2, v3
	v_cvt_pk_bf16_f32 v5, v10, v11
	ds_write_b16 v168, v4 offset:9216
	ds_write_b16_d16_hi v168, v4 offset:13568
	ds_write_b16 v168, v5 offset:17920
	ds_write_b16_d16_hi v168, v5 offset:22272
	ds_write_b16 v168, v0 offset:26624
	ds_write_b16_d16_hi v168, v0 offset:30976
	ds_write_b16 v168, v1 offset:35328
	ds_write_b16_d16_hi v168, v1 offset:39680
	v_lshl_add_u64 v[0:1], v[156:157], 0, v[64:65]
	global_load_dwordx4 v[126:129], v[0:1], off
	v_lshl_add_u64 v[0:1], v[158:159], 0, v[64:65]
	global_load_dwordx4 v[122:125], v[0:1], off
	v_lshl_add_u64 v[0:1], v[160:161], 0, v[64:65]
	global_load_dwordx4 v[118:121], v[0:1], off
	v_lshl_add_u64 v[0:1], v[154:155], 0, v[64:65]
	global_load_dwordx4 v[114:117], v[0:1], off
	s_and_b64 vcc, exec, s[38:39]
	v_mov_b32_e32 v0, 0
	v_mov_b32_e32 v1, 0
	v_mov_b32_e32 v2, 0
	v_mov_b32_e32 v3, 0
	v_mov_b32_e32 v4, 0
	v_mov_b32_e32 v5, 0
	v_mov_b32_e32 v6, 0
	v_mov_b32_e32 v7, 0
	v_mov_b32_e32 v8, 0
	v_mov_b32_e32 v9, 0
	v_mov_b32_e32 v10, 0
	v_mov_b32_e32 v11, 0
	v_mov_b32_e32 v12, 0
	v_mov_b32_e32 v13, 0
	v_mov_b32_e32 v14, 0
	v_mov_b32_e32 v15, 0
	s_waitcnt lgkmcnt(0)
	s_barrier
; #define LAS __attribute__((address_space(3)))
;     ...
;         const int d = 32 * dblk + r32;
;         const LAS unsigned char* ab = lds + BA_VNT + ((d & 7) * 16 + (d >> 3)) * 272 + hi * 16;
;         f32x16 acc[2];
; #pragma unroll
;         for (int j = 0; j < 2; ++j) {
;             const int tb = 2 * tbp + j;
; #pragma unroll
;             for (int r = 0; r < 16; ++r) acc[j][r] = 0.f;
; #pragma unroll
;             for (int ks = 0; ks < 8; ++ks) if (ks < 2 * (tb + 1)) {
;                 const bf16x8 af = *(const LAS bf16x8*)(ab + ks * 32);
;                 acc[j] = __builtin_amdgcn_mfma_f32_32x32x16_bf16(af, wf[j][ks], acc[j], 0, 0, 0);
;             }
	v_add_u32_e32 v250, v139, v140
	ds_read_b128 v[206:209], v250 offset:9216
	ds_read_b128 v[210:213], v250 offset:9248
	ds_read_b128 v[214:217], v250 offset:9280
	ds_read_b128 v[218:221], v250 offset:9312
	ds_read_b128 v[222:225], v250 offset:9344
	ds_read_b128 v[226:229], v250 offset:9376
	ds_read_b128 v[242:245], v250 offset:9408
	ds_read_b128 v[246:249], v250 offset:9440
	s_waitcnt lgkmcnt(0)
	s_cbranch_vccnz .LBB0_512
	v_mfma_f32_32x32x16_bf16 v[0:15], v[206:209], v[110:113], 0
.LBB0_512:
	s_and_b64 vcc, exec, s[38:39]
	s_cbranch_vccnz .LBB0_514
	v_mfma_f32_32x32x16_bf16 v[0:15], v[210:213], v[106:109], v[0:15]
.LBB0_514:
	s_and_b64 vcc, exec, s[36:37]
	s_cbranch_vccnz .LBB0_516
	v_mfma_f32_32x32x16_bf16 v[0:15], v[214:217], v[102:105], v[0:15]
.LBB0_516:
	v_cndmask_b32_e64 v16, 0, 1, s[2:3]
	v_cmp_ne_u32_e64 s[40:41], 1, v16
	s_andn2_b64 vcc, exec, s[2:3]
	s_cbranch_vccnz .LBB0_518
	v_mfma_f32_32x32x16_bf16 v[0:15], v[218:221], v[98:101], v[0:15]
.LBB0_518:
	s_and_b64 vcc, exec, s[36:37]
	s_cbranch_vccnz .LBB0_520
	v_mfma_f32_32x32x16_bf16 v[0:15], v[222:225], v[94:97], v[0:15]
.LBB0_520:
	v_cndmask_b32_e64 v16, 0, 1, s[8:9]
	v_cmp_ne_u32_e64 s[42:43], 1, v16
	s_andn2_b64 vcc, exec, s[8:9]
	s_cbranch_vccnz .LBB0_525
	v_mfma_f32_32x32x16_bf16 v[0:15], v[226:229], v[90:93], v[0:15]
	v_cndmask_b32_e64 v16, 0, 1, s[14:15]
	v_cmp_ne_u32_e64 s[44:45], 1, v16
	s_andn2_b64 vcc, exec, s[14:15]
	s_cbranch_vccz .LBB0_526

; #define LAS __attribute__((address_space(3)))
;     ...
; #pragma unroll
;             for (int ks = 0; ks < 8; ++ks) if (ks < 2 * (tb + 1)) {
;                 const bf16x8 af = *(const LAS bf16x8*)(ab + ks * 32);
;                 acc[j] = __builtin_amdgcn_mfma_f32_32x32x16_bf16(af, wf[j][ks], acc[j], 0, 0, 0);
;             }
.LBB0_523:
	v_mfma_f32_32x32x16_bf16 v[0:15], v[246:249], v[82:85], v[0:15]
	s_and_b64 vcc, exec, s[38:39]
	s_cbranch_vccz .LBB0_528

; #define LAS __attribute__((address_space(3)))
;     ...
; #pragma unroll
;             for (int ks = 0; ks < 8; ++ks) if (ks < 2 * (tb + 1)) {
;                 const bf16x8 af = *(const LAS bf16x8*)(ab + ks * 32);
;                 acc[j] = __builtin_amdgcn_mfma_f32_32x32x16_bf16(af, wf[j][ks], acc[j], 0, 0, 0);
;             }
.LBB0_526:
	v_mfma_f32_32x32x16_bf16 v[0:15], v[242:245], v[86:89], v[0:15]
	v_cndmask_b32_e64 v16, 0, 1, s[18:19]
	v_cmp_ne_u32_e64 s[46:47], 1, v16
	s_andn2_b64 vcc, exec, s[18:19]
	s_cbranch_vccz .LBB0_523

; #define LAS __attribute__((address_space(3)))
;     ...
; #pragma unroll
;         for (int j = 0; j < 2; ++j) {
;             const int tb = 2 * tbp + j;
; #pragma unroll
;             for (int r = 0; r < 16; ++r) acc[j][r] = 0.f;
; #pragma unroll
;             for (int ks = 0; ks < 8; ++ks) if (ks < 2 * (tb + 1)) {
;                 const bf16x8 af = *(const LAS bf16x8*)(ab + ks * 32);
;                 acc[j] = __builtin_amdgcn_mfma_f32_32x32x16_bf16(af, wf[j][ks], acc[j], 0, 0, 0);
;             }
.LBB0_528:
	v_mfma_f32_32x32x16_bf16 v[16:31], v[206:209], v[78:81], 0
	s_and_b64 vcc, exec, s[38:39]
	s_cbranch_vccnz .LBB0_530
.LBB0_529:
	v_mfma_f32_32x32x16_bf16 v[16:31], v[210:213], v[74:77], v[16:31]
.LBB0_530:
	s_and_b64 vcc, exec, s[38:39]
	s_cbranch_vccnz .LBB0_532
	v_mfma_f32_32x32x16_bf16 v[16:31], v[214:217], v[70:73], v[16:31]
.LBB0_532:
	s_and_b64 vcc, exec, s[38:39]
	s_cbranch_vccnz .LBB0_534
	v_mfma_f32_32x32x16_bf16 v[16:31], v[218:221], v[66:69], v[16:31]
.LBB0_534:
	s_and_b64 vcc, exec, s[36:37]
	s_cbranch_vccnz .LBB0_536
	v_mfma_f32_32x32x16_bf16 v[16:31], v[222:225], v[56:59], v[16:31]
.LBB0_536:
	s_and_b64 vcc, exec, s[36:37]
	s_cbranch_vccnz .LBB0_538
	v_mfma_f32_32x32x16_bf16 v[16:31], v[226:229], v[52:55], v[16:31]
.LBB0_538:
	s_and_b64 vcc, exec, s[36:37]
	s_cbranch_vccnz .LBB0_540
	v_mfma_f32_32x32x16_bf16 v[16:31], v[242:245], v[48:51], v[16:31]
.LBB0_540:
	s_and_b64 vcc, exec, s[36:37]
	s_cbranch_vccnz .LBB0_542
	v_mfma_f32_32x32x16_bf16 v[16:31], v[246:249], v[40:43], v[16:31]
